# dn_prep: wave 0's decay/beta address set-up and four loads issued ~400 instructions earlier (start of the l2-norm tail); the block only waits and copies
# baseline (speedup 1.0000x reference)
; __device__ __forceinline__ float silu_(float x) { return x * __builtin_amdgcn_rcpf(1.f + __expf(-x)); }
; #define SEC_BEGIN(id) unsigned long long _sec_t##id = 0; if ((id) == PROBE_SEC) { __builtin_amdgcn_s_barrier(); _sec_t##id = __builtin_amdgcn_s_memrealtime(); }
; __device__ __forceinline__ void phase_dn_prep(const KP kp, const int bid, const int G, int j, LAS unsigned char* lds, int tid0) {
;     ...
;         __syncthreads();
;         SEC_BEGIN(20)
;         {
;           const int t0 = 8 * wave; const bool first = (n == 0 && wave == 0);
;           float qa[8], qb[8], ka[8], kb[8];
; #pragma unroll
;           for (int part = 0; part < 3; ++part) { const int c = part * 1024 + h * 128 + 2 * lane;
;               const float w0a = cw[c], w0b = cw[c + 1], w1a = cw[3072 + c], w1b = cw[3072 + c + 1], w2a = cw[2 * 3072 + c], w2b = cw[2 * 3072 + c + 1], w3a = cw[3 * 3072 + c], w3b = cw[3 * 3072 + c + 1];
;               unsigned raw[11];
; #pragma unroll
;               for (int q = 0; q < 11; ++q) raw[q] = rawq[part][q];
;               if (first) { raw[0] = 0u; raw[1] = 0u; raw[2] = 0u; }
; #pragma unroll
;               for (int t = 0; t < 8; ++t) {
;                   const float ya = silu_(w0a * __uint_as_float(raw[t] << 16) + w1a * __uint_as_float(raw[t + 1] << 16) + w2a * __uint_as_float(raw[t + 2] << 16) + w3a * __uint_as_float(raw[t + 3] << 16));
;                   const float yb = silu_(w0b * __uint_as_float(raw[t] & 0xffff0000u) + w1b * __uint_as_float(raw[t + 1] & 0xffff0000u) + w2b * __uint_as_float(raw[t + 2] & 0xffff0000u) + w3b * __uint_as_float(raw[t + 3] & 0xffff0000u));
;                   if (part == 0) { qa[t] = ya; qb[t] = yb; } else if (part == 1) { ka[t] = ya; kb[t] = yb; } else { XL[(t0 + t) * 257 + 2 * lane] = ya; XL[(t0 + t) * 257 + 2 * lane + 1] = yb; } } }
.LBB0_554:
	s_bfe_u32 s3, s8, 0x50003
	s_and_b32 s2, s8, 7
	v_mov_b32_e32 v20, v183
	s_cmp_eq_u32 s3, 0
	s_cselect_b64 s[0:1], -1, 0
	s_waitcnt vmcnt(0)
	v_and_b32_e32 v68, 63, v20
	v_cmp_gt_u32_e32 vcc, 64, v20
	s_and_b64 s[0:1], s[0:1], vcc
	v_lshlrev_b32_e32 v2, 3, v68
	v_ashrrev_i32_e32 v72, 6, v20
	v_lshl_or_b32 v0, s2, 9, v2
	v_cndmask_b32_e64 v34, v40, 0, s[0:1]
	v_cndmask_b32_e64 v35, v39, 0, s[0:1]
	v_cndmask_b32_e64 v36, v19, 0, s[0:1]
	v_cndmask_b32_e64 v21, v51, 0, s[0:1]
	v_cndmask_b32_e64 v28, v50, 0, s[0:1]
	v_cndmask_b32_e64 v29, v49, 0, s[0:1]
	v_cndmask_b32_e64 v25, v62, 0, s[0:1]
	v_cndmask_b32_e64 v23, v61, 0, s[0:1]
	v_cndmask_b32_e64 v31, v60, 0, s[0:1]
	s_movk_i32 s0, 0x2020
	v_lshl_add_u64 v[16:17], s[46:47], 0, v[0:1]
	v_mul_lo_u32 v3, v72, s0
	s_movk_i32 s0, 0x3000
	v_add_co_u32_e64 v4, s[42:43], s0, v16
	s_movk_i32 s0, 0x6000
	s_nop 0
	v_addc_co_u32_e64 v5, s[42:43], 0, v17, s[42:43]
	v_add_co_u32_e64 v6, s[42:43], s0, v16
	s_mov_b32 s0, 0x9000
	s_nop 0
	v_addc_co_u32_e64 v7, s[42:43], 0, v17, s[42:43]
	v_add_co_u32_e64 v10, s[42:43], s0, v16
	s_barrier
	v_add3_u32 v37, s58, v2, v3
	global_load_dwordx2 v[2:3], v[4:5], off offset:-4096
	global_load_dwordx2 v[8:9], v[6:7], off offset:-4096
	v_addc_co_u32_e64 v11, s[42:43], 0, v17, s[42:43]
	s_mov_b32 s0, 0xb000
	v_add_co_u32_e64 v14, s[42:43], s0, v16
	global_load_dwordx2 v[12:13], v[10:11], off offset:-4096
	s_nop 0
	v_addc_co_u32_e64 v15, s[42:43], 0, v17, s[42:43]
	global_load_dwordx2 v[14:15], v[14:15], off
	v_lshlrev_b32_e32 v22, 16, v23
	v_and_b32_e32 v23, 0xffff0000, v23
	v_lshlrev_b32_e32 v30, 16, v31
	v_and_b32_e32 v31, 0xffff0000, v31
	v_lshlrev_b32_e32 v24, 16, v25
	v_and_b32_e32 v25, 0xffff0000, v25
	v_lshlrev_b32_e32 v26, 16, v63
	v_and_b32_e32 v27, 0xffff0000, v63
	v_add_u32_e32 v73, 0x404, v37
	s_waitcnt vmcnt(2)
	v_pk_mul_f32 v[32:33], v[8:9], v[22:23]
	s_nop 0
	v_pk_fma_f32 v[30:31], v[2:3], v[30:31], v[32:33]
	s_waitcnt vmcnt(1)
	v_pk_fma_f32 v[30:31], v[12:13], v[24:25], v[30:31]
	s_waitcnt vmcnt(0)
	v_pk_fma_f32 v[30:31], v[14:15], v[26:27], v[30:31]
	s_nop 0
	v_mul_f32_e32 v32, 0xbfb8aa3b, v31
	v_exp_f32_e32 v32, v32
	s_nop 0
	v_add_f32_e32 v32, 1.0, v32
	v_rcp_f32_e32 v33, v32
	v_mul_f32_e32 v32, 0xbfb8aa3b, v30
	v_exp_f32_e32 v32, v32
	s_nop 0
	v_add_f32_e32 v32, 1.0, v32
	v_rcp_f32_e32 v32, v32
	s_nop 0
	v_pk_mul_f32 v[30:31], v[30:31], v[32:33]
	v_pk_mul_f32 v[32:33], v[8:9], v[24:25]
	ds_write_b64 v37, v[30:31]
	v_pk_fma_f32 v[22:23], v[2:3], v[22:23], v[32:33]
	v_lshlrev_b32_e32 v30, 16, v64
	v_and_b32_e32 v31, 0xffff0000, v64
	v_pk_fma_f32 v[22:23], v[12:13], v[26:27], v[22:23]
	s_nop 0
	v_pk_fma_f32 v[22:23], v[14:15], v[30:31], v[22:23]
	s_nop 0
	v_mul_f32_e32 v32, 0xbfb8aa3b, v23
	v_exp_f32_e32 v32, v32
	s_nop 0
	v_add_f32_e32 v32, 1.0, v32
	v_rcp_f32_e32 v33, v32
	v_mul_f32_e32 v32, 0xbfb8aa3b, v22
	v_exp_f32_e32 v32, v32
	s_nop 0
	v_add_f32_e32 v32, 1.0, v32
	v_rcp_f32_e32 v32, v32
	s_nop 0
	v_pk_mul_f32 v[22:23], v[22:23], v[32:33]
	v_pk_mul_f32 v[32:33], v[8:9], v[26:27]
	ds_write2_b32 v73, v22, v23 offset1:1
	v_pk_fma_f32 v[24:25], v[2:3], v[24:25], v[32:33]
	v_lshlrev_b32_e32 v22, 16, v65
	v_and_b32_e32 v23, 0xffff0000, v65
	v_pk_fma_f32 v[24:25], v[12:13], v[30:31], v[24:25]
	v_add_u32_e32 v73, 0xc0c, v37
	v_pk_fma_f32 v[24:25], v[14:15], v[22:23], v[24:25]
	s_nop 0
	v_mul_f32_e32 v32, 0xbfb8aa3b, v25
	v_exp_f32_e32 v32, v32
	s_nop 0
	v_add_f32_e32 v32, 1.0, v32
	v_rcp_f32_e32 v33, v32
	v_mul_f32_e32 v32, 0xbfb8aa3b, v24
	v_exp_f32_e32 v32, v32
	s_nop 0
	v_add_f32_e32 v32, 1.0, v32
	v_rcp_f32_e32 v32, v32
	s_nop 0
	v_pk_mul_f32 v[24:25], v[24:25], v[32:33]
	v_pk_mul_f32 v[32:33], v[8:9], v[30:31]
	ds_write_b64 v37, v[24:25] offset:2056
	v_pk_fma_f32 v[26:27], v[2:3], v[26:27], v[32:33]
	v_lshlrev_b32_e32 v24, 16, v66
	v_and_b32_e32 v25, 0xffff0000, v66
	v_pk_fma_f32 v[26:27], v[12:13], v[22:23], v[26:27]
	s_nop 0
	v_pk_fma_f32 v[26:27], v[14:15], v[24:25], v[26:27]
	s_nop 0
	v_mul_f32_e32 v32, 0xbfb8aa3b, v27
	v_exp_f32_e32 v32, v32
	s_nop 0
	v_add_f32_e32 v32, 1.0, v32
	v_rcp_f32_e32 v33, v32
	v_mul_f32_e32 v32, 0xbfb8aa3b, v26
	v_exp_f32_e32 v32, v32
	s_nop 0
	v_add_f32_e32 v32, 1.0, v32
	v_rcp_f32_e32 v32, v32
	s_nop 0
	v_pk_mul_f32 v[26:27], v[26:27], v[32:33]
	v_pk_mul_f32 v[32:33], v[8:9], v[22:23]
	ds_write2_b32 v73, v26, v27 offset1:1
	v_pk_fma_f32 v[30:31], v[2:3], v[30:31], v[32:33]
	v_lshlrev_b32_e32 v26, 16, v67
	v_and_b32_e32 v27, 0xffff0000, v67
	v_pk_fma_f32 v[30:31], v[12:13], v[24:25], v[30:31]
	v_add_u32_e32 v73, 0x1414, v37
	v_pk_fma_f32 v[30:31], v[14:15], v[26:27], v[30:31]
	s_nop 0
	v_mul_f32_e32 v32, 0xbfb8aa3b, v31
	v_exp_f32_e32 v32, v32
	s_nop 0
	v_add_f32_e32 v32, 1.0, v32
	v_rcp_f32_e32 v33, v32
	v_mul_f32_e32 v32, 0xbfb8aa3b, v30
	v_exp_f32_e32 v32, v32
	s_nop 0
	v_add_f32_e32 v32, 1.0, v32
	v_rcp_f32_e32 v32, v32
	s_nop 0
	v_pk_mul_f32 v[30:31], v[30:31], v[32:33]
	v_pk_mul_f32 v[32:33], v[8:9], v[24:25]
	ds_write_b64 v37, v[30:31] offset:4112
	v_pk_fma_f32 v[22:23], v[2:3], v[22:23], v[32:33]
	v_lshlrev_b32_e32 v30, 16, v69
	v_and_b32_e32 v31, 0xffff0000, v69
	v_pk_fma_f32 v[22:23], v[12:13], v[26:27], v[22:23]
	s_nop 0
	v_pk_fma_f32 v[22:23], v[14:15], v[30:31], v[22:23]
	s_nop 0
	v_mul_f32_e32 v32, 0xbfb8aa3b, v23
	v_exp_f32_e32 v32, v32
	s_nop 0
	v_add_f32_e32 v32, 1.0, v32
	v_rcp_f32_e32 v33, v32
	v_mul_f32_e32 v32, 0xbfb8aa3b, v22
	v_exp_f32_e32 v32, v32
	s_nop 0
	v_add_f32_e32 v32, 1.0, v32
	v_rcp_f32_e32 v32, v32
	s_nop 0
	v_pk_mul_f32 v[22:23], v[22:23], v[32:33]
	v_pk_mul_f32 v[32:33], v[8:9], v[26:27]
	ds_write2_b32 v73, v22, v23 offset1:1
	v_pk_fma_f32 v[24:25], v[2:3], v[24:25], v[32:33]
; #define LAS __attribute__((address_space(3)))
; __device__ __forceinline__ unsigned pk2(float lo, float hi) { return cvtpk(lo, hi); }
; __device__ __forceinline__ float silu_(float x) { return x * __builtin_amdgcn_rcpf(1.f + __expf(-x)); }
; __device__ __forceinline__ void phase_dn_prep(const KP kp, const int bid, const int G, int j, LAS unsigned char* lds, int tid0) {
;     ...
;           for (int part = 0; part < 3; ++part) { const int c = part * 1024 + h * 128 + 2 * lane;
;               const float w0a = cw[c], w0b = cw[c + 1], w1a = cw[3072 + c], w1b = cw[3072 + c + 1], w2a = cw[2 * 3072 + c], w2b = cw[2 * 3072 + c + 1], w3a = cw[3 * 3072 + c], w3b = cw[3 * 3072 + c + 1];
;               unsigned raw[11];
; #pragma unroll
;               for (int q = 0; q < 11; ++q) raw[q] = rawq[part][q];
;               if (first) { raw[0] = 0u; raw[1] = 0u; raw[2] = 0u; }
; #pragma unroll
;               for (int t = 0; t < 8; ++t) {
;                   const float ya = silu_(w0a * __uint_as_float(raw[t] << 16) + w1a * __uint_as_float(raw[t + 1] << 16) + w2a * __uint_as_float(raw[t + 2] << 16) + w3a * __uint_as_float(raw[t + 3] << 16));
;                   const float yb = silu_(w0b * __uint_as_float(raw[t] & 0xffff0000u) + w1b * __uint_as_float(raw[t + 1] & 0xffff0000u) + w2b * __uint_as_float(raw[t + 2] & 0xffff0000u) + w3b * __uint_as_float(raw[t + 3] & 0xffff0000u));
;                   if (part == 0) { qa[t] = ya; qb[t] = yb; } else if (part == 1) { ka[t] = ya; kb[t] = yb; } else { XL[(t0 + t) * 257 + 2 * lane] = ya; XL[(t0 + t) * 257 + 2 * lane + 1] = yb; } } }
; #pragma unroll
;           for (int t = 0; t < 8; ++t) { const float scq = rsqrtf(wave_sum(qa[t] * qa[t] + qb[t] * qb[t]) + 1e-6f) * 0.08838834764831845f, sck = rsqrtf(wave_sum(ka[t] * ka[t] + kb[t] * kb[t]) + 1e-6f);
;               *(LAS unsigned*)(Qb + (t0 + t) * 136 + 2 * lane) = pk2(qa[t] * scq, qb[t] * scq); *(LAS unsigned*)(Kb + (t0 + t) * 136 + 2 * lane) = pk2(ka[t] * sck, kb[t] * sck); } }
	v_lshlrev_b32_e32 v22, 16, v70
	v_and_b32_e32 v23, 0xffff0000, v70
	v_pk_fma_f32 v[24:25], v[12:13], v[30:31], v[24:25]
	v_pk_mul_f32 v[8:9], v[8:9], v[30:31]
	v_pk_fma_f32 v[24:25], v[14:15], v[22:23], v[24:25]
	v_pk_fma_f32 v[2:3], v[2:3], v[26:27], v[8:9]
	v_mul_f32_e32 v32, 0xbfb8aa3b, v25
	v_exp_f32_e32 v32, v32
	v_pk_fma_f32 v[2:3], v[12:13], v[22:23], v[2:3]
	v_lshlrev_b32_e32 v26, 16, v35
	v_and_b32_e32 v27, 0xffff0000, v35
	v_add_f32_e32 v32, 1.0, v32
	v_rcp_f32_e32 v33, v32
	v_mul_f32_e32 v32, 0xbfb8aa3b, v24
	v_exp_f32_e32 v32, v32
	v_lshlrev_b32_e32 v22, 16, v41
	v_and_b32_e32 v23, 0xffff0000, v41
	v_and_b32_e32 v35, 0xffff0000, v28
	v_add_f32_e32 v32, 1.0, v32
	v_rcp_f32_e32 v32, v32
	v_mov_b32_e32 v31, v1
	v_mov_b32_e32 v73, v1
	v_pk_mul_f32 v[24:25], v[24:25], v[32:33]
	ds_write_b64 v37, v[24:25] offset:6168
	v_lshlrev_b32_e32 v24, 16, v71
	v_and_b32_e32 v25, 0xffff0000, v71
	v_pk_fma_f32 v[2:3], v[14:15], v[24:25], v[2:3]
	v_add_u32_e32 v32, 0x1c1c, v37
	v_mul_f32_e32 v8, 0xbfb8aa3b, v3
	v_exp_f32_e32 v8, v8
	v_lshlrev_b32_e32 v24, 16, v34
	v_and_b32_e32 v25, 0xffff0000, v34
	v_lshlrev_b32_e32 v14, 2, v68
	v_add_f32_e32 v8, 1.0, v8
	v_rcp_f32_e32 v9, v8
	v_mul_f32_e32 v8, 0xbfb8aa3b, v2
	v_exp_f32_e32 v8, v8
	v_lshlrev_b32_e32 v34, 16, v28
	v_and_b32_e32 v33, 0xffff0000, v29
	v_and_b32_e32 v37, 0xffff0000, v21
	v_add_f32_e32 v8, 1.0, v8
	v_rcp_f32_e32 v8, v8
	s_nop 0
	v_pk_mul_f32 v[2:3], v[2:3], v[8:9]
	ds_write2_b32 v32, v2, v3 offset1:1
	global_load_dwordx2 v[2:3], v0, s[46:47]
	global_load_dwordx2 v[8:9], v[4:5], off
	s_nop 0
	global_load_dwordx2 v[4:5], v[6:7], off
	s_nop 0
	global_load_dwordx2 v[6:7], v[10:11], off
	v_lshlrev_b32_e32 v10, 16, v36
	v_and_b32_e32 v11, 0xffff0000, v36
	v_lshlrev_b32_e32 v32, 16, v29
	v_lshlrev_b32_e32 v36, 16, v21
	s_waitcnt vmcnt(2)
	v_pk_mul_f32 v[12:13], v[8:9], v[26:27]
	s_nop 0
	v_pk_fma_f32 v[10:11], v[2:3], v[10:11], v[12:13]
	s_waitcnt vmcnt(1)
	v_pk_fma_f32 v[10:11], v[4:5], v[24:25], v[10:11]
	s_waitcnt vmcnt(0)
	v_pk_fma_f32 v[10:11], v[6:7], v[22:23], v[10:11]
	s_nop 0
	v_mul_f32_e32 v0, 0xbfb8aa3b, v10
	v_exp_f32_e32 v0, v0
	s_nop 0
	v_add_f32_e32 v0, 1.0, v0
	v_rcp_f32_e32 v12, v0
	v_mul_f32_e32 v0, 0xbfb8aa3b, v11
	v_exp_f32_e32 v0, v0
	s_nop 0
	v_add_f32_e32 v0, 1.0, v0
	v_rcp_f32_e32 v13, v0
	s_nop 0
	v_pk_mul_f32 v[10:11], v[10:11], v[12:13]
	s_nop 0
	v_pk_mul_f32 v[12:13], v[10:11], v[10:11]
	s_nop 0
	v_add_f32_e32 v0, v12, v13
	v_mov_b32_e32 v12, v1
	s_nop 0
	v_add_f32_dpp v0, v0, v0 quad_perm:[1,0,3,2] row_mask:0xf bank_mask:0xf bound_ctrl:1
	s_nop 1
	v_add_f32_dpp v0, v0, v0 quad_perm:[2,3,0,1] row_mask:0xf bank_mask:0xf bound_ctrl:1
	s_nop 1
	v_add_f32_dpp v0, v0, v0 row_half_mirror row_mask:0xf bank_mask:0xf bound_ctrl:1
	s_nop 1
	v_add_f32_dpp v0, v0, v0 row_mirror row_mask:0xf bank_mask:0xf bound_ctrl:1
	s_nop 1
	v_mov_b32_dpp v12, v0 row_bcast:15 row_mask:0xa bank_mask:0xf
	v_add_f32_e32 v0, v0, v12
	v_mov_b32_e32 v12, v1
	s_nop 1
	v_mov_b32_dpp v12, v0 row_bcast:31 row_mask:0xc bank_mask:0xf
	v_add_f32_e32 v0, v0, v12
	s_nop 0
	v_readlane_b32 s0, v0, 63
	s_nop 1
	v_add_f32_e32 v0, s0, v214
	v_cmp_gt_f32_e64 s[42:43], s65, v0
	v_mul_f32_e32 v12, 0x4b800000, v0
	s_movk_i32 s0, 0x880
	v_cndmask_b32_e64 v0, v0, v12, s[42:43]
	v_rsq_f32_e32 v0, v0
	s_nop 0
	v_mul_f32_e32 v12, 0x45800000, v0
	v_cndmask_b32_e64 v0, v0, v12, s[42:43]
	v_mul_f32_e32 v0, 0x3db504f3, v0
	v_pk_mul_f32 v[10:11], v[10:11], v[0:1] op_sel_hi:[1,0]
	v_mul_lo_u32 v0, v72, s0
	s_movk_i32 s0, 0x1000
	v_cvt_pk_bf16_f32 v30, v10, v11
	v_add_co_u32_e64 v10, s[42:43], s0, v16
	s_movk_i32 s0, 0x7000
	s_nop 0
	v_addc_co_u32_e64 v11, s[42:43], 0, v17, s[42:43]
	v_add_co_u32_e64 v12, s[42:43], s88, v16
	v_add3_u32 v0, 0, v14, v0
	s_nop 0
	v_addc_co_u32_e64 v13, s[42:43], 0, v17, s[42:43]
	v_add_co_u32_e64 v14, s[42:43], s0, v16
	global_load_dwordx2 v[10:11], v[10:11], off
	s_nop 0
	v_addc_co_u32_e64 v15, s[42:43], 0, v17, s[42:43]
	global_load_dwordx2 v[12:13], v[12:13], off
	s_mov_b32 s0, 0xa000
	v_add_co_u32_e64 v16, s[42:43], s0, v16
	global_load_dwordx2 v[14:15], v[14:15], off
	s_nop 0
	v_addc_co_u32_e64 v17, s[42:43], 0, v17, s[42:43]
	global_load_dwordx2 v[16:17], v[16:17], off
	s_waitcnt vmcnt(2)
	v_pk_mul_f32 v[28:29], v[12:13], v[34:35]
	s_nop 0
	v_pk_fma_f32 v[28:29], v[10:11], v[32:33], v[28:29]
	v_lshlrev_b32_e32 v32, 16, v52
	v_and_b32_e32 v33, 0xffff0000, v52
	s_waitcnt vmcnt(1)
	v_pk_fma_f32 v[28:29], v[14:15], v[36:37], v[28:29]
	s_waitcnt vmcnt(0)
; #define LAS __attribute__((address_space(3)))
; __device__ __forceinline__ unsigned pk2(float lo, float hi) { return cvtpk(lo, hi); }
; __device__ __forceinline__ float silu_(float x) { return x * __builtin_amdgcn_rcpf(1.f + __expf(-x)); }
; __device__ __forceinline__ void phase_dn_prep(const KP kp, const int bid, const int G, int j, LAS unsigned char* lds, int tid0) {
;     ...
;               for (int t = 0; t < 8; ++t) {
;                   const float ya = silu_(w0a * __uint_as_float(raw[t] << 16) + w1a * __uint_as_float(raw[t + 1] << 16) + w2a * __uint_as_float(raw[t + 2] << 16) + w3a * __uint_as_float(raw[t + 3] << 16));
;                   const float yb = silu_(w0b * __uint_as_float(raw[t] & 0xffff0000u) + w1b * __uint_as_float(raw[t + 1] & 0xffff0000u) + w2b * __uint_as_float(raw[t + 2] & 0xffff0000u) + w3b * __uint_as_float(raw[t + 3] & 0xffff0000u));
;                   if (part == 0) { qa[t] = ya; qb[t] = yb; } else if (part == 1) { ka[t] = ya; kb[t] = yb; } else { XL[(t0 + t) * 257 + 2 * lane] = ya; XL[(t0 + t) * 257 + 2 * lane + 1] = yb; } } }
; #pragma unroll
;           for (int t = 0; t < 8; ++t) { const float scq = rsqrtf(wave_sum(qa[t] * qa[t] + qb[t] * qb[t]) + 1e-6f) * 0.08838834764831845f, sck = rsqrtf(wave_sum(ka[t] * ka[t] + kb[t] * kb[t]) + 1e-6f);
;               *(LAS unsigned*)(Qb + (t0 + t) * 136 + 2 * lane) = pk2(qa[t] * scq, qb[t] * scq); *(LAS unsigned*)(Kb + (t0 + t) * 136 + 2 * lane) = pk2(ka[t] * sck, kb[t] * sck); } }
	v_pk_fma_f32 v[28:29], v[16:17], v[32:33], v[28:29]
	s_nop 0
	v_mul_f32_e32 v21, 0xbfb8aa3b, v28
	v_exp_f32_e32 v21, v21
	s_nop 0
	v_add_f32_e32 v21, 1.0, v21
	v_rcp_f32_e32 v74, v21
	v_mul_f32_e32 v21, 0xbfb8aa3b, v29
	v_exp_f32_e32 v21, v21
	s_nop 0
	v_add_f32_e32 v21, 1.0, v21
	v_rcp_f32_e32 v75, v21
	s_nop 0
	v_pk_mul_f32 v[28:29], v[28:29], v[74:75]
	s_nop 0
	v_pk_mul_f32 v[74:75], v[28:29], v[28:29]
	s_nop 0
	v_add_f32_e32 v21, v74, v75
	s_nop 1
	v_add_f32_dpp v21, v21, v21 quad_perm:[1,0,3,2] row_mask:0xf bank_mask:0xf bound_ctrl:1
	s_nop 1
	v_add_f32_dpp v21, v21, v21 quad_perm:[2,3,0,1] row_mask:0xf bank_mask:0xf bound_ctrl:1
	s_nop 1
	v_add_f32_dpp v21, v21, v21 row_half_mirror row_mask:0xf bank_mask:0xf bound_ctrl:1
	s_nop 1
	v_add_f32_dpp v21, v21, v21 row_mirror row_mask:0xf bank_mask:0xf bound_ctrl:1
	s_nop 1
	v_mov_b32_dpp v31, v21 row_bcast:15 row_mask:0xa bank_mask:0xf
	v_add_f32_e32 v21, v21, v31
	v_mov_b32_e32 v31, v1
	s_nop 1
	v_mov_b32_dpp v31, v21 row_bcast:31 row_mask:0xc bank_mask:0xf
	v_add_f32_e32 v21, v21, v31
	s_nop 0
	v_readlane_b32 s0, v21, 63
	s_nop 1
	v_add_f32_e32 v21, s0, v214
	v_cmp_gt_f32_e64 s[42:43], s65, v21
	v_mul_f32_e32 v31, 0x4b800000, v21
	s_nop 0
	v_cndmask_b32_e64 v21, v21, v31, s[42:43]
	v_rsq_f32_e32 v21, v21
	s_nop 0
	v_mul_f32_e32 v31, 0x45800000, v21
	v_cndmask_b32_e64 v74, v21, v31, s[42:43]
	v_pk_mul_f32 v[28:29], v[28:29], v[74:75] op_sel_hi:[1,0]
	v_pk_mul_f32 v[74:75], v[8:9], v[24:25]
	v_cvt_pk_bf16_f32 v21, v28, v29
	v_pk_fma_f32 v[26:27], v[2:3], v[26:27], v[74:75]
	v_lshlrev_b32_e32 v28, 16, v42
	v_and_b32_e32 v29, 0xffff0000, v42
	v_pk_fma_f32 v[26:27], v[4:5], v[22:23], v[26:27]
	s_nop 0
	v_pk_fma_f32 v[26:27], v[6:7], v[28:29], v[26:27]
	s_nop 0
	v_mul_f32_e32 v31, 0xbfb8aa3b, v26
	v_exp_f32_e32 v31, v31
	s_nop 0
	v_add_f32_e32 v31, 1.0, v31
	v_rcp_f32_e32 v74, v31
	v_mul_f32_e32 v31, 0xbfb8aa3b, v27
	v_exp_f32_e32 v31, v31
	s_nop 0
	v_add_f32_e32 v31, 1.0, v31
	v_rcp_f32_e32 v75, v31
	s_nop 0
	v_pk_mul_f32 v[26:27], v[26:27], v[74:75]
	s_nop 0
	v_pk_mul_f32 v[74:75], v[26:27], v[26:27]
	s_nop 0
	v_add_f32_e32 v31, v74, v75
	s_nop 1
	v_add_f32_dpp v31, v31, v31 quad_perm:[1,0,3,2] row_mask:0xf bank_mask:0xf bound_ctrl:1
	s_nop 1
	v_add_f32_dpp v31, v31, v31 quad_perm:[2,3,0,1] row_mask:0xf bank_mask:0xf bound_ctrl:1
	s_nop 1
	v_add_f32_dpp v31, v31, v31 row_half_mirror row_mask:0xf bank_mask:0xf bound_ctrl:1
	s_nop 1
	v_add_f32_dpp v31, v31, v31 row_mirror row_mask:0xf bank_mask:0xf bound_ctrl:1
	s_nop 1
	v_mov_b32_dpp v73, v31 row_bcast:15 row_mask:0xa bank_mask:0xf
	v_add_f32_e32 v31, v31, v73
	v_mov_b32_e32 v73, v1
	s_nop 1
	v_mov_b32_dpp v73, v31 row_bcast:31 row_mask:0xc bank_mask:0xf
	v_add_f32_e32 v31, v31, v73
	s_nop 0
	v_readlane_b32 s0, v31, 63
	s_nop 1
	v_add_f32_e32 v31, s0, v214
	v_cmp_gt_f32_e64 s[42:43], s65, v31
	v_mul_f32_e32 v73, 0x4b800000, v31
	s_nop 0
	v_cndmask_b32_e64 v31, v31, v73, s[42:43]
	v_rsq_f32_e32 v31, v31
	s_nop 0
	v_mul_f32_e32 v73, 0x45800000, v31
	v_cndmask_b32_e64 v31, v31, v73, s[42:43]
	v_mul_f32_e32 v74, 0x3db504f3, v31
	v_pk_mul_f32 v[26:27], v[26:27], v[74:75] op_sel_hi:[1,0]
	v_add_u32_e32 v74, 0x9000, v0
	v_cvt_pk_bf16_f32 v26, v26, v27
	v_add_u32_e32 v27, 0x8c00, v0
	ds_write2_b32 v27, v30, v26 offset0:128 offset1:196
	v_pk_mul_f32 v[30:31], v[12:13], v[36:37]
	v_lshlrev_b32_e32 v26, 16, v53
	v_pk_fma_f32 v[30:31], v[10:11], v[34:35], v[30:31]
	v_and_b32_e32 v27, 0xffff0000, v53
	v_pk_fma_f32 v[30:31], v[14:15], v[32:33], v[30:31]
	v_add_u32_e32 v75, 0x4c00, v0
	v_pk_fma_f32 v[30:31], v[16:17], v[26:27], v[30:31]
	s_nop 0
	v_mul_f32_e32 v34, 0xbfb8aa3b, v30
	v_mul_f32_e32 v35, 0xbfb8aa3b, v31
	v_exp_f32_e32 v34, v34
	v_exp_f32_e32 v35, v35
	v_add_f32_e32 v34, 1.0, v34
	v_add_f32_e32 v35, 1.0, v35
	v_rcp_f32_e32 v34, v34
	v_rcp_f32_e32 v35, v35
	s_nop 0
	v_pk_mul_f32 v[30:31], v[30:31], v[34:35]
	s_nop 0
	v_pk_mul_f32 v[34:35], v[30:31], v[30:31]
	s_nop 0
	v_add_f32_e32 v34, v34, v35
	v_mov_b32_e32 v35, v1
	s_nop 0
	v_add_f32_dpp v34, v34, v34 quad_perm:[1,0,3,2] row_mask:0xf bank_mask:0xf bound_ctrl:1
	s_nop 1
	v_add_f32_dpp v34, v34, v34 quad_perm:[2,3,0,1] row_mask:0xf bank_mask:0xf bound_ctrl:1
	s_nop 1
	v_add_f32_dpp v34, v34, v34 row_half_mirror row_mask:0xf bank_mask:0xf bound_ctrl:1
	s_nop 1
	v_add_f32_dpp v34, v34, v34 row_mirror row_mask:0xf bank_mask:0xf bound_ctrl:1
	s_nop 1
	v_mov_b32_dpp v35, v34 row_bcast:15 row_mask:0xa bank_mask:0xf
	v_add_f32_e32 v34, v34, v35
	v_mov_b32_e32 v35, v1
	s_nop 1
	v_mov_b32_dpp v35, v34 row_bcast:31 row_mask:0xc bank_mask:0xf
	v_add_f32_e32 v34, v34, v35
	s_nop 0
	v_readlane_b32 s0, v34, 63
	s_nop 1
	v_add_f32_e32 v34, s0, v214
	v_cmp_gt_f32_e64 s[42:43], s65, v34
	v_mul_f32_e32 v35, 0x4b800000, v34
	s_nop 0
	v_cndmask_b32_e64 v34, v34, v35, s[42:43]
	v_rsq_f32_e32 v34, v34
	s_nop 0
	v_mul_f32_e32 v35, 0x45800000, v34
	v_cndmask_b32_e64 v34, v34, v35, s[42:43]
	v_pk_mul_f32 v[30:31], v[30:31], v[34:35] op_sel_hi:[1,0]
	v_lshlrev_b32_e32 v34, 16, v43
	v_cvt_pk_bf16_f32 v30, v30, v31
	v_add_u32_e32 v31, 0x4800, v0
	ds_write2_b32 v31, v21, v30 offset0:128 offset1:196
	v_pk_mul_f32 v[30:31], v[8:9], v[22:23]
	v_and_b32_e32 v35, 0xffff0000, v43
	v_pk_fma_f32 v[24:25], v[2:3], v[24:25], v[30:31]
	s_nop 0
	v_pk_fma_f32 v[24:25], v[4:5], v[28:29], v[24:25]
	s_nop 0
	v_pk_fma_f32 v[24:25], v[6:7], v[34:35], v[24:25]
	s_nop 0
	v_mul_f32_e32 v21, 0xbfb8aa3b, v24
	v_exp_f32_e32 v21, v21
	s_nop 0
	v_add_f32_e32 v21, 1.0, v21
	v_rcp_f32_e32 v30, v21
	v_mul_f32_e32 v21, 0xbfb8aa3b, v25
	v_exp_f32_e32 v21, v21
	s_nop 0
	v_add_f32_e32 v21, 1.0, v21
	v_rcp_f32_e32 v31, v21
	s_nop 0
; #define LAS __attribute__((address_space(3)))
; __device__ __forceinline__ unsigned pk2(float lo, float hi) { return cvtpk(lo, hi); }
; __device__ __forceinline__ float silu_(float x) { return x * __builtin_amdgcn_rcpf(1.f + __expf(-x)); }
; __device__ __forceinline__ void phase_dn_prep(const KP kp, const int bid, const int G, int j, LAS unsigned char* lds, int tid0) {
;     ...
;               for (int t = 0; t < 8; ++t) {
;                   const float ya = silu_(w0a * __uint_as_float(raw[t] << 16) + w1a * __uint_as_float(raw[t + 1] << 16) + w2a * __uint_as_float(raw[t + 2] << 16) + w3a * __uint_as_float(raw[t + 3] << 16));
;                   const float yb = silu_(w0b * __uint_as_float(raw[t] & 0xffff0000u) + w1b * __uint_as_float(raw[t + 1] & 0xffff0000u) + w2b * __uint_as_float(raw[t + 2] & 0xffff0000u) + w3b * __uint_as_float(raw[t + 3] & 0xffff0000u));
;                   if (part == 0) { qa[t] = ya; qb[t] = yb; } else if (part == 1) { ka[t] = ya; kb[t] = yb; } else { XL[(t0 + t) * 257 + 2 * lane] = ya; XL[(t0 + t) * 257 + 2 * lane + 1] = yb; } } }
; #pragma unroll
;           for (int t = 0; t < 8; ++t) { const float scq = rsqrtf(wave_sum(qa[t] * qa[t] + qb[t] * qb[t]) + 1e-6f) * 0.08838834764831845f, sck = rsqrtf(wave_sum(ka[t] * ka[t] + kb[t] * kb[t]) + 1e-6f);
;               *(LAS unsigned*)(Qb + (t0 + t) * 136 + 2 * lane) = pk2(qa[t] * scq, qb[t] * scq); *(LAS unsigned*)(Kb + (t0 + t) * 136 + 2 * lane) = pk2(ka[t] * sck, kb[t] * sck); } }
	v_pk_mul_f32 v[24:25], v[24:25], v[30:31]
	s_nop 0
	v_pk_mul_f32 v[30:31], v[24:25], v[24:25]
	s_nop 0
	v_add_f32_e32 v21, v30, v31
	v_mov_b32_e32 v30, v1
	s_nop 0
	v_add_f32_dpp v21, v21, v21 quad_perm:[1,0,3,2] row_mask:0xf bank_mask:0xf bound_ctrl:1
	s_nop 1
	v_add_f32_dpp v21, v21, v21 quad_perm:[2,3,0,1] row_mask:0xf bank_mask:0xf bound_ctrl:1
	s_nop 1
	v_add_f32_dpp v21, v21, v21 row_half_mirror row_mask:0xf bank_mask:0xf bound_ctrl:1
	s_nop 1
	v_add_f32_dpp v21, v21, v21 row_mirror row_mask:0xf bank_mask:0xf bound_ctrl:1
	s_nop 1
	v_mov_b32_dpp v30, v21 row_bcast:15 row_mask:0xa bank_mask:0xf
	v_add_f32_e32 v21, v21, v30
	v_mov_b32_e32 v30, v1
	s_nop 1
	v_mov_b32_dpp v30, v21 row_bcast:31 row_mask:0xc bank_mask:0xf
	v_add_f32_e32 v21, v21, v30
	s_nop 0
	v_readlane_b32 s0, v21, 63
	s_nop 1
	v_add_f32_e32 v21, s0, v214
	v_cmp_gt_f32_e64 s[42:43], s65, v21
	v_mul_f32_e32 v30, 0x4b800000, v21
	s_nop 0
	v_cndmask_b32_e64 v21, v21, v30, s[42:43]
	v_rsq_f32_e32 v21, v21
	s_nop 0
	v_mul_f32_e32 v30, 0x45800000, v21
	v_cndmask_b32_e64 v21, v21, v30, s[42:43]
	v_mul_f32_e32 v30, 0x3db504f3, v21
	v_pk_mul_f32 v[24:25], v[24:25], v[30:31] op_sel_hi:[1,0]
	v_lshlrev_b32_e32 v30, 16, v54
	v_cvt_pk_bf16_f32 v21, v24, v25
	v_pk_mul_f32 v[24:25], v[12:13], v[32:33]
	v_and_b32_e32 v31, 0xffff0000, v54
	v_pk_fma_f32 v[24:25], v[10:11], v[36:37], v[24:25]
	s_nop 0
	v_pk_fma_f32 v[24:25], v[14:15], v[26:27], v[24:25]
	s_nop 0
	v_pk_fma_f32 v[24:25], v[16:17], v[30:31], v[24:25]
	s_nop 0
	v_mul_f32_e32 v36, 0xbfb8aa3b, v24
	v_mul_f32_e32 v37, 0xbfb8aa3b, v25
	v_exp_f32_e32 v36, v36
	v_exp_f32_e32 v37, v37
	v_add_f32_e32 v36, 1.0, v36
	v_add_f32_e32 v37, 1.0, v37
	v_rcp_f32_e32 v36, v36
	v_rcp_f32_e32 v37, v37
	s_nop 0
	v_pk_mul_f32 v[24:25], v[24:25], v[36:37]
	s_nop 0
	v_pk_mul_f32 v[36:37], v[24:25], v[24:25]
	s_nop 0
	v_add_f32_e32 v36, v36, v37
	v_mov_b32_e32 v37, v1
	s_nop 0
	v_add_f32_dpp v36, v36, v36 quad_perm:[1,0,3,2] row_mask:0xf bank_mask:0xf bound_ctrl:1
	s_nop 1
	v_add_f32_dpp v36, v36, v36 quad_perm:[2,3,0,1] row_mask:0xf bank_mask:0xf bound_ctrl:1
	s_nop 1
	v_add_f32_dpp v36, v36, v36 row_half_mirror row_mask:0xf bank_mask:0xf bound_ctrl:1
	s_nop 1
	v_add_f32_dpp v36, v36, v36 row_mirror row_mask:0xf bank_mask:0xf bound_ctrl:1
	s_nop 1
	v_mov_b32_dpp v37, v36 row_bcast:15 row_mask:0xa bank_mask:0xf
	v_add_f32_e32 v36, v36, v37
	v_mov_b32_e32 v37, v1
	s_nop 1
	v_mov_b32_dpp v37, v36 row_bcast:31 row_mask:0xc bank_mask:0xf
	v_add_f32_e32 v36, v36, v37
	s_nop 0
	v_readlane_b32 s0, v36, 63
	s_nop 1
	v_add_f32_e32 v36, s0, v214
	v_cmp_gt_f32_e64 s[42:43], s65, v36
	v_mul_f32_e32 v37, 0x4b800000, v36
	s_nop 0
	v_cndmask_b32_e64 v36, v36, v37, s[42:43]
	v_rsq_f32_e32 v36, v36
	s_nop 0
	v_mul_f32_e32 v37, 0x45800000, v36
	v_cndmask_b32_e64 v36, v36, v37, s[42:43]
	v_pk_mul_f32 v[24:25], v[24:25], v[36:37] op_sel_hi:[1,0]
	v_pk_mul_f32 v[36:37], v[8:9], v[28:29]
	v_cvt_pk_bf16_f32 v73, v24, v25
	v_pk_fma_f32 v[22:23], v[2:3], v[22:23], v[36:37]
	v_lshlrev_b32_e32 v24, 16, v44
	v_and_b32_e32 v25, 0xffff0000, v44
	v_pk_fma_f32 v[22:23], v[4:5], v[34:35], v[22:23]
	s_nop 0
	v_pk_fma_f32 v[22:23], v[6:7], v[24:25], v[22:23]
	s_nop 0
	v_mul_f32_e32 v36, 0xbfb8aa3b, v22
	v_mul_f32_e32 v37, 0xbfb8aa3b, v23
	v_exp_f32_e32 v36, v36
	v_exp_f32_e32 v37, v37
	v_add_f32_e32 v36, 1.0, v36
	v_add_f32_e32 v37, 1.0, v37
	v_rcp_f32_e32 v36, v36
	v_rcp_f32_e32 v37, v37
	s_nop 0
	v_pk_mul_f32 v[22:23], v[22:23], v[36:37]
	s_nop 0
	v_pk_mul_f32 v[36:37], v[22:23], v[22:23]
	s_nop 0
	v_add_f32_e32 v36, v36, v37
	v_mov_b32_e32 v37, v1
	s_nop 0
	v_add_f32_dpp v36, v36, v36 quad_perm:[1,0,3,2] row_mask:0xf bank_mask:0xf bound_ctrl:1
	s_nop 1
	v_add_f32_dpp v36, v36, v36 quad_perm:[2,3,0,1] row_mask:0xf bank_mask:0xf bound_ctrl:1
	s_nop 1
	v_add_f32_dpp v36, v36, v36 row_half_mirror row_mask:0xf bank_mask:0xf bound_ctrl:1
	s_nop 1
	v_add_f32_dpp v36, v36, v36 row_mirror row_mask:0xf bank_mask:0xf bound_ctrl:1
	s_nop 1
	v_mov_b32_dpp v37, v36 row_bcast:15 row_mask:0xa bank_mask:0xf
	v_add_f32_e32 v36, v36, v37
	v_mov_b32_e32 v37, v1
	s_nop 1
	v_mov_b32_dpp v37, v36 row_bcast:31 row_mask:0xc bank_mask:0xf
	v_add_f32_e32 v36, v36, v37
	s_nop 0
	v_readlane_b32 s0, v36, 63
	s_nop 1
	v_add_f32_e32 v36, s0, v214
	v_cmp_gt_f32_e64 s[42:43], s65, v36
	v_mul_f32_e32 v37, 0x4b800000, v36
	s_nop 0
	v_cndmask_b32_e64 v36, v36, v37, s[42:43]
	v_rsq_f32_e32 v36, v36
	s_nop 0
	v_mul_f32_e32 v37, 0x45800000, v36
	v_cndmask_b32_e64 v36, v36, v37, s[42:43]
	v_mul_f32_e32 v36, 0x3db504f3, v36
	v_pk_mul_f32 v[22:23], v[22:23], v[36:37] op_sel_hi:[1,0]
	v_pk_mul_f32 v[36:37], v[12:13], v[26:27]
	v_cvt_pk_bf16_f32 v22, v22, v23
	v_pk_fma_f32 v[32:33], v[10:11], v[32:33], v[36:37]
	ds_write2_b32 v74, v21, v22 offset0:8 offset1:76
	v_lshlrev_b32_e32 v22, 16, v55
	v_and_b32_e32 v23, 0xffff0000, v55
	v_pk_fma_f32 v[32:33], v[14:15], v[30:31], v[32:33]
	s_nop 0
	v_pk_fma_f32 v[32:33], v[16:17], v[22:23], v[32:33]
	s_nop 0
	v_mul_f32_e32 v21, 0xbfb8aa3b, v32
	v_exp_f32_e32 v21, v21
	s_nop 0
	v_add_f32_e32 v21, 1.0, v21
	v_rcp_f32_e32 v36, v21
	v_mul_f32_e32 v21, 0xbfb8aa3b, v33
	v_exp_f32_e32 v21, v21
	s_nop 0
	v_add_f32_e32 v21, 1.0, v21
	v_rcp_f32_e32 v37, v21
	s_nop 0
	v_pk_mul_f32 v[32:33], v[32:33], v[36:37]
	s_nop 0
	v_pk_mul_f32 v[36:37], v[32:33], v[32:33]
	s_nop 0
	v_add_f32_e32 v21, v36, v37
	v_mov_b32_e32 v36, v1
	s_nop 0
	v_add_f32_dpp v21, v21, v21 quad_perm:[1,0,3,2] row_mask:0xf bank_mask:0xf bound_ctrl:1
	s_nop 1
	v_add_f32_dpp v21, v21, v21 quad_perm:[2,3,0,1] row_mask:0xf bank_mask:0xf bound_ctrl:1
	s_nop 1
	v_add_f32_dpp v21, v21, v21 row_half_mirror row_mask:0xf bank_mask:0xf bound_ctrl:1
; #define LAS __attribute__((address_space(3)))
; __device__ __forceinline__ float bf2f(bf16 b) { return __uint_as_float(((unsigned)b) << 16); }
; __device__ __forceinline__ unsigned pk2(float lo, float hi) { return cvtpk(lo, hi); }
; __device__ __forceinline__ float silu_(float x) { return x * __builtin_amdgcn_rcpf(1.f + __expf(-x)); }
; __device__ __forceinline__ float softplus_(float x) { return x > 15.f ? x : (x < -15.f ? __expf(x) : __logf(1.f + __expf(x))); }
; __device__ __forceinline__ void phase_dn_prep(const KP kp, const int bid, const int G, int j, LAS unsigned char* lds, int tid0) {
;     ...
;               for (int t = 0; t < 8; ++t) {
;                   const float ya = silu_(w0a * __uint_as_float(raw[t] << 16) + w1a * __uint_as_float(raw[t + 1] << 16) + w2a * __uint_as_float(raw[t + 2] << 16) + w3a * __uint_as_float(raw[t + 3] << 16));
;                   const float yb = silu_(w0b * __uint_as_float(raw[t] & 0xffff0000u) + w1b * __uint_as_float(raw[t + 1] & 0xffff0000u) + w2b * __uint_as_float(raw[t + 2] & 0xffff0000u) + w3b * __uint_as_float(raw[t + 3] & 0xffff0000u));
;                   if (part == 0) { qa[t] = ya; qb[t] = yb; } else if (part == 1) { ka[t] = ya; kb[t] = yb; } else { XL[(t0 + t) * 257 + 2 * lane] = ya; XL[(t0 + t) * 257 + 2 * lane + 1] = yb; } } }
; #pragma unroll
;           for (int t = 0; t < 8; ++t) { const float scq = rsqrtf(wave_sum(qa[t] * qa[t] + qb[t] * qb[t]) + 1e-6f) * 0.08838834764831845f, sck = rsqrtf(wave_sum(ka[t] * ka[t] + kb[t] * kb[t]) + 1e-6f);
;               *(LAS unsigned*)(Qb + (t0 + t) * 136 + 2 * lane) = pk2(qa[t] * scq, qb[t] * scq); *(LAS unsigned*)(Kb + (t0 + t) * 136 + 2 * lane) = pk2(ka[t] * sck, kb[t] * sck); } }
;         if (wave == 0) { const size_t ro = (size_t)(row0 + lane) * NAB;
;             float gv = -__expf(kp.in(15)[j * 8 + h]) * softplus_(bf2f(U[ro + 7176 + h]) + kp.in(16)[j * 8 + h]);
	s_nop 1
	v_add_f32_dpp v21, v21, v21 row_mirror row_mask:0xf bank_mask:0xf bound_ctrl:1
	s_nop 1
	v_mov_b32_dpp v36, v21 row_bcast:15 row_mask:0xa bank_mask:0xf
	v_add_f32_e32 v21, v21, v36
	v_mov_b32_e32 v36, v1
	s_nop 1
	v_mov_b32_dpp v36, v21 row_bcast:31 row_mask:0xc bank_mask:0xf
	v_add_f32_e32 v21, v21, v36
	s_nop 0
	v_readlane_b32 s0, v21, 63
	s_nop 1
	v_add_f32_e32 v21, s0, v214
	v_cmp_gt_f32_e64 s[42:43], s65, v21
	v_mul_f32_e32 v36, 0x4b800000, v21
	s_nop 0
	v_cndmask_b32_e64 v21, v21, v36, s[42:43]
	v_rsq_f32_e32 v21, v21
	s_nop 0
	v_mul_f32_e32 v36, 0x45800000, v21
	v_cndmask_b32_e64 v36, v21, v36, s[42:43]
	v_pk_mul_f32 v[32:33], v[32:33], v[36:37] op_sel_hi:[1,0]
	v_pk_mul_f32 v[36:37], v[8:9], v[34:35]
	v_cvt_pk_bf16_f32 v21, v32, v33
	v_pk_fma_f32 v[28:29], v[2:3], v[28:29], v[36:37]
	v_lshlrev_b32_e32 v32, 16, v45
	v_and_b32_e32 v33, 0xffff0000, v45
	v_pk_fma_f32 v[28:29], v[4:5], v[24:25], v[28:29]
	ds_write2_b32 v75, v73, v21 offset0:8 offset1:76
	v_pk_fma_f32 v[28:29], v[6:7], v[32:33], v[28:29]
	s_nop 0
	v_mul_f32_e32 v21, 0xbfb8aa3b, v28
	v_exp_f32_e32 v21, v21
	s_nop 0
	v_add_f32_e32 v21, 1.0, v21
	v_rcp_f32_e32 v36, v21
	v_mul_f32_e32 v21, 0xbfb8aa3b, v29
	v_exp_f32_e32 v21, v21
	s_nop 0
	v_add_f32_e32 v21, 1.0, v21
	v_rcp_f32_e32 v37, v21
	s_nop 0
	v_pk_mul_f32 v[28:29], v[28:29], v[36:37]
	s_nop 0
	v_pk_mul_f32 v[36:37], v[28:29], v[28:29]
	s_nop 0
	v_add_f32_e32 v21, v36, v37
	v_mov_b32_e32 v36, v1
	s_nop 0
	v_add_f32_dpp v21, v21, v21 quad_perm:[1,0,3,2] row_mask:0xf bank_mask:0xf bound_ctrl:1
	s_nop 1
	v_add_f32_dpp v21, v21, v21 quad_perm:[2,3,0,1] row_mask:0xf bank_mask:0xf bound_ctrl:1
	s_nop 1
	v_add_f32_dpp v21, v21, v21 row_half_mirror row_mask:0xf bank_mask:0xf bound_ctrl:1
	s_nop 1
	s_load_dwordx4 s[16:19], s[60:61], 0x78
	s_lshl_b32 s3, s3, 6
	s_and_b32 s4, s59, 0xfffff800
	s_or_b32 s3, s3, s4
	s_or_b32 s4, s2, s6
	s_ashr_i32 s5, s4, 31
	s_lshl_b64 s[4:5], s[4:5], 2
	s_waitcnt lgkmcnt(0)
	s_add_u32 s10, s16, s4
	v_or_b32_e32 v80, s3, v20
	s_addc_u32 s11, s17, s5
	v_mov_b64_e32 v[78:79], s[62:63]
	s_movk_i32 s3, 0x3a00
	global_load_dword v76, v1, s[10:11]
	v_mad_i64_i32 v[78:79], s[10:11], v80, s3, v[78:79]
	s_lshl_b32 s38, s2, 1
	v_lshl_add_u64 v[78:79], v[78:79], 0, s[38:39]
	s_mov_b32 s100, 0x3000
	s_mov_b32 s101, 0
	s_add_u32 s2, s18, s4
	v_lshl_add_u64 v[80:81], v[78:79], 0, s[100:101]
	global_load_ushort v82, v[80:81], off offset:2064
	global_load_ushort v77, v[80:81], off offset:2048
	s_addc_u32 s3, s19, s5
	global_load_dword v83, v1, s[2:3]
	v_add_f32_dpp v21, v21, v21 row_mirror row_mask:0xf bank_mask:0xf bound_ctrl:1
	s_nop 1
	v_mov_b32_dpp v36, v21 row_bcast:15 row_mask:0xa bank_mask:0xf
	v_add_f32_e32 v21, v21, v36
	v_mov_b32_e32 v36, v1
	s_nop 1
	v_mov_b32_dpp v36, v21 row_bcast:31 row_mask:0xc bank_mask:0xf
	v_add_f32_e32 v21, v21, v36
	s_nop 0
	v_readlane_b32 s0, v21, 63
	s_nop 1
	v_add_f32_e32 v21, s0, v214
	v_cmp_gt_f32_e64 s[42:43], s65, v21
	v_mul_f32_e32 v36, 0x4b800000, v21
	s_nop 0
	v_cndmask_b32_e64 v21, v21, v36, s[42:43]
	v_rsq_f32_e32 v21, v21
	s_nop 0
	v_mul_f32_e32 v36, 0x45800000, v21
	v_cndmask_b32_e64 v21, v21, v36, s[42:43]
	v_mul_f32_e32 v36, 0x3db504f3, v21
	v_pk_mul_f32 v[28:29], v[28:29], v[36:37] op_sel_hi:[1,0]
	v_pk_mul_f32 v[36:37], v[12:13], v[30:31]
	v_cvt_pk_bf16_f32 v21, v28, v29
	v_pk_fma_f32 v[26:27], v[10:11], v[26:27], v[36:37]
	v_lshlrev_b32_e32 v28, 16, v56
	v_and_b32_e32 v29, 0xffff0000, v56
	v_pk_fma_f32 v[26:27], v[14:15], v[22:23], v[26:27]
	s_nop 0
	v_pk_fma_f32 v[26:27], v[16:17], v[28:29], v[26:27]
	s_nop 0
	v_mul_f32_e32 v36, 0xbfb8aa3b, v26
	v_mul_f32_e32 v37, 0xbfb8aa3b, v27
	v_exp_f32_e32 v36, v36
	v_exp_f32_e32 v37, v37
	v_add_f32_e32 v36, 1.0, v36
	v_add_f32_e32 v37, 1.0, v37
	v_rcp_f32_e32 v36, v36
	v_rcp_f32_e32 v37, v37
	s_nop 0
	v_pk_mul_f32 v[26:27], v[26:27], v[36:37]
	s_nop 0
	v_pk_mul_f32 v[36:37], v[26:27], v[26:27]
	s_nop 0
	v_add_f32_e32 v36, v36, v37
	v_mov_b32_e32 v37, v1
	s_nop 0
	v_add_f32_dpp v36, v36, v36 quad_perm:[1,0,3,2] row_mask:0xf bank_mask:0xf bound_ctrl:1
	s_nop 1
	v_add_f32_dpp v36, v36, v36 quad_perm:[2,3,0,1] row_mask:0xf bank_mask:0xf bound_ctrl:1
	s_nop 1
	v_add_f32_dpp v36, v36, v36 row_half_mirror row_mask:0xf bank_mask:0xf bound_ctrl:1
	s_nop 1
	v_add_f32_dpp v36, v36, v36 row_mirror row_mask:0xf bank_mask:0xf bound_ctrl:1
	s_nop 1
	v_mov_b32_dpp v37, v36 row_bcast:15 row_mask:0xa bank_mask:0xf
	v_add_f32_e32 v36, v36, v37
	v_mov_b32_e32 v37, v1
	s_nop 1
	v_mov_b32_dpp v37, v36 row_bcast:31 row_mask:0xc bank_mask:0xf
	v_add_f32_e32 v36, v36, v37
	s_nop 0
	v_readlane_b32 s0, v36, 63
	s_nop 1
	v_add_f32_e32 v36, s0, v214
	v_cmp_gt_f32_e64 s[42:43], s65, v36
	v_mul_f32_e32 v37, 0x4b800000, v36
	s_nop 0
	v_cndmask_b32_e64 v36, v36, v37, s[42:43]
	v_rsq_f32_e32 v36, v36
	s_nop 0
	v_mul_f32_e32 v37, 0x45800000, v36
	v_cndmask_b32_e64 v36, v36, v37, s[42:43]
	v_pk_mul_f32 v[26:27], v[26:27], v[36:37] op_sel_hi:[1,0]
	v_pk_mul_f32 v[36:37], v[8:9], v[24:25]
	v_cvt_pk_bf16_f32 v73, v26, v27
	v_pk_fma_f32 v[34:35], v[2:3], v[34:35], v[36:37]
	v_lshlrev_b32_e32 v26, 16, v46
	v_and_b32_e32 v27, 0xffff0000, v46
	v_pk_fma_f32 v[34:35], v[4:5], v[32:33], v[34:35]
	s_nop 0
	v_pk_fma_f32 v[34:35], v[6:7], v[26:27], v[34:35]
	s_nop 0
	v_mul_f32_e32 v36, 0xbfb8aa3b, v34
	v_mul_f32_e32 v37, 0xbfb8aa3b, v35
	v_exp_f32_e32 v36, v36
	v_exp_f32_e32 v37, v37
	v_add_f32_e32 v36, 1.0, v36
	v_add_f32_e32 v37, 1.0, v37
	v_rcp_f32_e32 v36, v36
	v_rcp_f32_e32 v37, v37
	s_nop 0
	v_pk_mul_f32 v[34:35], v[34:35], v[36:37]
	s_nop 0
	v_pk_mul_f32 v[36:37], v[34:35], v[34:35]
	s_nop 0
	v_add_f32_e32 v36, v36, v37
	v_mov_b32_e32 v37, v1
; #define LAS __attribute__((address_space(3)))
; __device__ __forceinline__ unsigned pk2(float lo, float hi) { return cvtpk(lo, hi); }
; __device__ __forceinline__ float silu_(float x) { return x * __builtin_amdgcn_rcpf(1.f + __expf(-x)); }
; __device__ __forceinline__ void phase_dn_prep(const KP kp, const int bid, const int G, int j, LAS unsigned char* lds, int tid0) {
;     ...
;               for (int t = 0; t < 8; ++t) {
;                   const float ya = silu_(w0a * __uint_as_float(raw[t] << 16) + w1a * __uint_as_float(raw[t + 1] << 16) + w2a * __uint_as_float(raw[t + 2] << 16) + w3a * __uint_as_float(raw[t + 3] << 16));
;                   const float yb = silu_(w0b * __uint_as_float(raw[t] & 0xffff0000u) + w1b * __uint_as_float(raw[t + 1] & 0xffff0000u) + w2b * __uint_as_float(raw[t + 2] & 0xffff0000u) + w3b * __uint_as_float(raw[t + 3] & 0xffff0000u));
;                   if (part == 0) { qa[t] = ya; qb[t] = yb; } else if (part == 1) { ka[t] = ya; kb[t] = yb; } else { XL[(t0 + t) * 257 + 2 * lane] = ya; XL[(t0 + t) * 257 + 2 * lane + 1] = yb; } } }
; #pragma unroll
;           for (int t = 0; t < 8; ++t) { const float scq = rsqrtf(wave_sum(qa[t] * qa[t] + qb[t] * qb[t]) + 1e-6f) * 0.08838834764831845f, sck = rsqrtf(wave_sum(ka[t] * ka[t] + kb[t] * kb[t]) + 1e-6f);
;               *(LAS unsigned*)(Qb + (t0 + t) * 136 + 2 * lane) = pk2(qa[t] * scq, qb[t] * scq); *(LAS unsigned*)(Kb + (t0 + t) * 136 + 2 * lane) = pk2(ka[t] * sck, kb[t] * sck); } }
	s_nop 0
	v_add_f32_dpp v36, v36, v36 quad_perm:[1,0,3,2] row_mask:0xf bank_mask:0xf bound_ctrl:1
	s_nop 1
	v_add_f32_dpp v36, v36, v36 quad_perm:[2,3,0,1] row_mask:0xf bank_mask:0xf bound_ctrl:1
	s_nop 1
	v_add_f32_dpp v36, v36, v36 row_half_mirror row_mask:0xf bank_mask:0xf bound_ctrl:1
	s_nop 1
	v_add_f32_dpp v36, v36, v36 row_mirror row_mask:0xf bank_mask:0xf bound_ctrl:1
	s_nop 1
	v_mov_b32_dpp v37, v36 row_bcast:15 row_mask:0xa bank_mask:0xf
	v_add_f32_e32 v36, v36, v37
	v_mov_b32_e32 v37, v1
	s_nop 1
	v_mov_b32_dpp v37, v36 row_bcast:31 row_mask:0xc bank_mask:0xf
	v_add_f32_e32 v36, v36, v37
	s_nop 0
	v_readlane_b32 s0, v36, 63
	s_nop 1
	v_add_f32_e32 v36, s0, v214
	v_cmp_gt_f32_e64 s[42:43], s65, v36
	v_mul_f32_e32 v37, 0x4b800000, v36
	s_nop 0
	v_cndmask_b32_e64 v36, v36, v37, s[42:43]
	v_rsq_f32_e32 v36, v36
	s_nop 0
	v_mul_f32_e32 v37, 0x45800000, v36
	v_cndmask_b32_e64 v36, v36, v37, s[42:43]
	v_mul_f32_e32 v36, 0x3db504f3, v36
	v_pk_mul_f32 v[34:35], v[34:35], v[36:37] op_sel_hi:[1,0]
	v_pk_mul_f32 v[36:37], v[12:13], v[22:23]
	v_cvt_pk_bf16_f32 v34, v34, v35
	v_pk_fma_f32 v[30:31], v[10:11], v[30:31], v[36:37]
	ds_write2_b32 v74, v21, v34 offset0:144 offset1:212
	v_lshlrev_b32_e32 v34, 16, v57
	v_and_b32_e32 v35, 0xffff0000, v57
	v_pk_fma_f32 v[30:31], v[14:15], v[28:29], v[30:31]
	s_nop 0
	v_pk_fma_f32 v[30:31], v[16:17], v[34:35], v[30:31]
	s_nop 0
	v_mul_f32_e32 v21, 0xbfb8aa3b, v30
	v_exp_f32_e32 v21, v21
	s_nop 0
	v_add_f32_e32 v21, 1.0, v21
	v_rcp_f32_e32 v36, v21
	v_mul_f32_e32 v21, 0xbfb8aa3b, v31
	v_exp_f32_e32 v21, v21
	s_nop 0
	v_add_f32_e32 v21, 1.0, v21
	v_rcp_f32_e32 v37, v21
	s_nop 0
	v_pk_mul_f32 v[30:31], v[30:31], v[36:37]
	s_nop 0
	v_pk_mul_f32 v[36:37], v[30:31], v[30:31]
	s_nop 0
	v_add_f32_e32 v21, v36, v37
	v_mov_b32_e32 v36, v1
	s_nop 0
	v_add_f32_dpp v21, v21, v21 quad_perm:[1,0,3,2] row_mask:0xf bank_mask:0xf bound_ctrl:1
	s_nop 1
	v_add_f32_dpp v21, v21, v21 quad_perm:[2,3,0,1] row_mask:0xf bank_mask:0xf bound_ctrl:1
	s_nop 1
	v_add_f32_dpp v21, v21, v21 row_half_mirror row_mask:0xf bank_mask:0xf bound_ctrl:1
	s_nop 1
	v_add_f32_dpp v21, v21, v21 row_mirror row_mask:0xf bank_mask:0xf bound_ctrl:1
	s_nop 1
	v_mov_b32_dpp v36, v21 row_bcast:15 row_mask:0xa bank_mask:0xf
	v_add_f32_e32 v21, v21, v36
	v_mov_b32_e32 v36, v1
	s_nop 1
	v_mov_b32_dpp v36, v21 row_bcast:31 row_mask:0xc bank_mask:0xf
	v_add_f32_e32 v21, v21, v36
	s_nop 0
	v_readlane_b32 s0, v21, 63
	s_nop 1
	v_add_f32_e32 v21, s0, v214
	v_cmp_gt_f32_e64 s[42:43], s65, v21
	v_mul_f32_e32 v36, 0x4b800000, v21
	s_nop 0
	v_cndmask_b32_e64 v21, v21, v36, s[42:43]
	v_rsq_f32_e32 v21, v21
	s_nop 0
	v_mul_f32_e32 v36, 0x45800000, v21
	v_cndmask_b32_e64 v36, v21, v36, s[42:43]
	v_pk_mul_f32 v[30:31], v[30:31], v[36:37] op_sel_hi:[1,0]
	v_pk_mul_f32 v[36:37], v[8:9], v[32:33]
	v_cvt_pk_bf16_f32 v21, v30, v31
	v_pk_fma_f32 v[24:25], v[2:3], v[24:25], v[36:37]
	v_lshlrev_b32_e32 v30, 16, v47
	v_and_b32_e32 v31, 0xffff0000, v47
	v_pk_fma_f32 v[24:25], v[4:5], v[26:27], v[24:25]
	ds_write2_b32 v75, v73, v21 offset0:144 offset1:212
	v_pk_fma_f32 v[24:25], v[6:7], v[30:31], v[24:25]
	v_pk_mul_f32 v[8:9], v[8:9], v[26:27]
	v_mul_f32_e32 v21, 0xbfb8aa3b, v24
	v_exp_f32_e32 v21, v21
	v_pk_fma_f32 v[2:3], v[2:3], v[32:33], v[8:9]
	v_add_f32_e32 v21, 1.0, v21
	v_rcp_f32_e32 v36, v21
	v_mul_f32_e32 v21, 0xbfb8aa3b, v25
	v_exp_f32_e32 v21, v21
	v_pk_fma_f32 v[2:3], v[4:5], v[30:31], v[2:3]
	v_add_f32_e32 v21, 1.0, v21
	v_rcp_f32_e32 v37, v21
	s_nop 0
	v_pk_mul_f32 v[24:25], v[24:25], v[36:37]
	s_nop 0
	v_pk_mul_f32 v[36:37], v[24:25], v[24:25]
	s_nop 0
	v_add_f32_e32 v21, v36, v37
	v_mov_b32_e32 v36, v1
	s_nop 0
	v_add_f32_dpp v21, v21, v21 quad_perm:[1,0,3,2] row_mask:0xf bank_mask:0xf bound_ctrl:1
	s_nop 1
	v_add_f32_dpp v21, v21, v21 quad_perm:[2,3,0,1] row_mask:0xf bank_mask:0xf bound_ctrl:1
	s_nop 1
	v_add_f32_dpp v21, v21, v21 row_half_mirror row_mask:0xf bank_mask:0xf bound_ctrl:1
	s_nop 1
	v_add_f32_dpp v21, v21, v21 row_mirror row_mask:0xf bank_mask:0xf bound_ctrl:1
	s_nop 1
	v_mov_b32_dpp v36, v21 row_bcast:15 row_mask:0xa bank_mask:0xf
	v_add_f32_e32 v21, v21, v36
	v_mov_b32_e32 v36, v1
	s_nop 1
	v_mov_b32_dpp v36, v21 row_bcast:31 row_mask:0xc bank_mask:0xf
	v_add_f32_e32 v21, v21, v36
	s_nop 0
	v_readlane_b32 s0, v21, 63
	s_nop 1
	v_add_f32_e32 v21, s0, v214
	v_cmp_gt_f32_e64 s[42:43], s65, v21
	v_mul_f32_e32 v36, 0x4b800000, v21
	s_nop 0
	v_cndmask_b32_e64 v21, v21, v36, s[42:43]
	v_rsq_f32_e32 v21, v21
	s_nop 0
	v_mul_f32_e32 v36, 0x45800000, v21
	v_cndmask_b32_e64 v21, v21, v36, s[42:43]
	v_mul_f32_e32 v36, 0x3db504f3, v21
	v_pk_mul_f32 v[24:25], v[24:25], v[36:37] op_sel_hi:[1,0]
	v_pk_mul_f32 v[36:37], v[12:13], v[28:29]
	v_cvt_pk_bf16_f32 v21, v24, v25
	v_pk_fma_f32 v[22:23], v[10:11], v[22:23], v[36:37]
	v_lshlrev_b32_e32 v24, 16, v58
	v_and_b32_e32 v25, 0xffff0000, v58
	v_pk_fma_f32 v[22:23], v[14:15], v[34:35], v[22:23]
	s_nop 0
	v_pk_fma_f32 v[22:23], v[16:17], v[24:25], v[22:23]
	s_nop 0
	v_mul_f32_e32 v36, 0xbfb8aa3b, v22
	v_mul_f32_e32 v37, 0xbfb8aa3b, v23
	v_exp_f32_e32 v36, v36
	v_exp_f32_e32 v37, v37
	v_add_f32_e32 v36, 1.0, v36
	v_add_f32_e32 v37, 1.0, v37
	v_rcp_f32_e32 v36, v36
	v_rcp_f32_e32 v37, v37
	s_nop 0
	v_pk_mul_f32 v[22:23], v[22:23], v[36:37]
	s_nop 0
	v_pk_mul_f32 v[36:37], v[22:23], v[22:23]
; #define LAS __attribute__((address_space(3)))
; __device__ __forceinline__ float bf2f(bf16 b) { return __uint_as_float(((unsigned)b) << 16); }
; __device__ __forceinline__ unsigned pk2(float lo, float hi) { return cvtpk(lo, hi); }
; __device__ __forceinline__ float softplus_(float x) { return x > 15.f ? x : (x < -15.f ? __expf(x) : __logf(1.f + __expf(x))); }
; __device__ __forceinline__ void phase_dn_prep(const KP kp, const int bid, const int G, int j, LAS unsigned char* lds, int tid0) {
;     ...
;           for (int t = 0; t < 8; ++t) { const float scq = rsqrtf(wave_sum(qa[t] * qa[t] + qb[t] * qb[t]) + 1e-6f) * 0.08838834764831845f, sck = rsqrtf(wave_sum(ka[t] * ka[t] + kb[t] * kb[t]) + 1e-6f);
;               *(LAS unsigned*)(Qb + (t0 + t) * 136 + 2 * lane) = pk2(qa[t] * scq, qb[t] * scq); *(LAS unsigned*)(Kb + (t0 + t) * 136 + 2 * lane) = pk2(ka[t] * sck, kb[t] * sck); } }
;         if (wave == 0) { const size_t ro = (size_t)(row0 + lane) * NAB;
;             float gv = -__expf(kp.in(15)[j * 8 + h]) * softplus_(bf2f(U[ro + 7176 + h]) + kp.in(16)[j * 8 + h]);
	s_nop 0
	v_add_f32_e32 v36, v36, v37
	v_mov_b32_e32 v37, v1
	s_nop 0
	v_add_f32_dpp v36, v36, v36 quad_perm:[1,0,3,2] row_mask:0xf bank_mask:0xf bound_ctrl:1
	s_nop 1
	v_add_f32_dpp v36, v36, v36 quad_perm:[2,3,0,1] row_mask:0xf bank_mask:0xf bound_ctrl:1
	s_nop 1
	v_add_f32_dpp v36, v36, v36 row_half_mirror row_mask:0xf bank_mask:0xf bound_ctrl:1
	s_nop 1
	v_add_f32_dpp v36, v36, v36 row_mirror row_mask:0xf bank_mask:0xf bound_ctrl:1
	s_nop 1
	v_mov_b32_dpp v37, v36 row_bcast:15 row_mask:0xa bank_mask:0xf
	v_add_f32_e32 v36, v36, v37
	v_mov_b32_e32 v37, v1
	s_nop 1
	v_mov_b32_dpp v37, v36 row_bcast:31 row_mask:0xc bank_mask:0xf
	v_add_f32_e32 v36, v36, v37
	s_nop 0
	v_readlane_b32 s0, v36, 63
	s_nop 1
	v_add_f32_e32 v36, s0, v214
	v_cmp_gt_f32_e64 s[42:43], s65, v36
	v_mul_f32_e32 v37, 0x4b800000, v36
	s_nop 0
	v_cndmask_b32_e64 v36, v36, v37, s[42:43]
	v_rsq_f32_e32 v36, v36
	s_nop 0
	v_mul_f32_e32 v37, 0x45800000, v36
	v_cndmask_b32_e64 v36, v36, v37, s[42:43]
	v_pk_mul_f32 v[22:23], v[22:23], v[36:37] op_sel_hi:[1,0]
	s_nop 0
	v_cvt_pk_bf16_f32 v36, v22, v23
	v_lshlrev_b32_e32 v22, 16, v48
	v_and_b32_e32 v23, 0xffff0000, v48
	v_pk_fma_f32 v[2:3], v[6:7], v[22:23], v[2:3]
	s_nop 0
	v_mul_f32_e32 v4, 0xbfb8aa3b, v2
	v_mul_f32_e32 v5, 0xbfb8aa3b, v3
	v_exp_f32_e32 v4, v4
	v_exp_f32_e32 v5, v5
	v_add_f32_e32 v4, 1.0, v4
	v_add_f32_e32 v5, 1.0, v5
	v_rcp_f32_e32 v4, v4
	v_rcp_f32_e32 v5, v5
	s_nop 0
	v_pk_mul_f32 v[2:3], v[2:3], v[4:5]
	s_nop 0
	v_pk_mul_f32 v[4:5], v[2:3], v[2:3]
	s_nop 0
	v_add_f32_e32 v4, v4, v5
	v_mov_b32_e32 v5, v1
	s_nop 0
	v_add_f32_dpp v4, v4, v4 quad_perm:[1,0,3,2] row_mask:0xf bank_mask:0xf bound_ctrl:1
	s_nop 1
	v_add_f32_dpp v4, v4, v4 quad_perm:[2,3,0,1] row_mask:0xf bank_mask:0xf bound_ctrl:1
	s_nop 1
	v_add_f32_dpp v4, v4, v4 row_half_mirror row_mask:0xf bank_mask:0xf bound_ctrl:1
	s_nop 1
	v_add_f32_dpp v4, v4, v4 row_mirror row_mask:0xf bank_mask:0xf bound_ctrl:1
	s_nop 1
	v_mov_b32_dpp v5, v4 row_bcast:15 row_mask:0xa bank_mask:0xf
	v_add_f32_e32 v4, v4, v5
	v_mov_b32_e32 v5, v1
	s_nop 1
	v_mov_b32_dpp v5, v4 row_bcast:31 row_mask:0xc bank_mask:0xf
	v_add_f32_e32 v4, v4, v5
	s_nop 0
	v_readlane_b32 s0, v4, 63
	s_nop 1
	v_add_f32_e32 v4, s0, v214
	v_cmp_gt_f32_e64 s[42:43], s65, v4
	v_mul_f32_e32 v5, 0x4b800000, v4
	s_nop 0
	v_cndmask_b32_e64 v4, v4, v5, s[42:43]
	v_rsq_f32_e32 v4, v4
	s_nop 0
	v_mul_f32_e32 v5, 0x45800000, v4
	v_cndmask_b32_e64 v4, v4, v5, s[42:43]
	v_mul_f32_e32 v4, 0x3db504f3, v4
	v_pk_mul_f32 v[2:3], v[2:3], v[4:5] op_sel_hi:[1,0]
	v_pk_mul_f32 v[4:5], v[12:13], v[34:35]
	v_cvt_pk_bf16_f32 v2, v2, v3
	v_add_u32_e32 v3, 0x9400, v0
	v_pk_fma_f32 v[4:5], v[10:11], v[28:29], v[4:5]
	ds_write2_b32 v3, v21, v2 offset0:24 offset1:92
	v_lshlrev_b32_e32 v2, 16, v59
	v_and_b32_e32 v3, 0xffff0000, v59
	v_pk_fma_f32 v[4:5], v[14:15], v[24:25], v[4:5]
	v_add_u32_e32 v0, 0x5000, v0
	v_pk_fma_f32 v[2:3], v[16:17], v[2:3], v[4:5]
	s_nop 0
	v_mul_f32_e32 v4, 0xbfb8aa3b, v2
	v_mul_f32_e32 v5, 0xbfb8aa3b, v3
	v_exp_f32_e32 v4, v4
	v_exp_f32_e32 v5, v5
	v_add_f32_e32 v4, 1.0, v4
	v_add_f32_e32 v5, 1.0, v5
	v_rcp_f32_e32 v4, v4
	v_rcp_f32_e32 v5, v5
	s_nop 0
	v_pk_mul_f32 v[2:3], v[2:3], v[4:5]
	s_nop 0
	v_pk_mul_f32 v[4:5], v[2:3], v[2:3]
	s_nop 0
	v_add_f32_e32 v4, v4, v5
	v_mov_b32_e32 v5, v1
	s_nop 0
	v_add_f32_dpp v4, v4, v4 quad_perm:[1,0,3,2] row_mask:0xf bank_mask:0xf bound_ctrl:1
	s_nop 1
	v_add_f32_dpp v4, v4, v4 quad_perm:[2,3,0,1] row_mask:0xf bank_mask:0xf bound_ctrl:1
	s_nop 1
	v_add_f32_dpp v4, v4, v4 row_half_mirror row_mask:0xf bank_mask:0xf bound_ctrl:1
	s_nop 1
	v_add_f32_dpp v4, v4, v4 row_mirror row_mask:0xf bank_mask:0xf bound_ctrl:1
	s_nop 1
	v_mov_b32_dpp v5, v4 row_bcast:15 row_mask:0xa bank_mask:0xf
	v_add_f32_e32 v4, v4, v5
	v_mov_b32_e32 v5, v1
	s_nop 1
	v_mov_b32_dpp v5, v4 row_bcast:31 row_mask:0xc bank_mask:0xf
	v_add_f32_e32 v4, v4, v5
	s_nop 0
	v_readlane_b32 s0, v4, 63
	s_nop 1
	v_add_f32_e32 v4, s0, v214
	v_cmp_gt_f32_e64 s[42:43], s65, v4
	v_mul_f32_e32 v5, 0x4b800000, v4
	s_nop 0
	v_cndmask_b32_e64 v4, v4, v5, s[42:43]
	v_rsq_f32_e32 v4, v4
	s_nop 0
	v_mul_f32_e32 v5, 0x45800000, v4
	v_cndmask_b32_e64 v4, v4, v5, s[42:43]
	v_pk_mul_f32 v[2:3], v[2:3], v[4:5] op_sel_hi:[1,0]
	s_nop 0
	v_cvt_pk_bf16_f32 v2, v2, v3
	ds_write2_b32 v0, v36, v2 offset0:24 offset1:92
	s_and_saveexec_b64 s[0:1], vcc
	s_cbranch_execz .LBB0_560
	s_waitcnt vmcnt(0)
	v_mov_b32_e32 v0, v76
	v_mov_b32_e32 v4, v82
	v_mov_b32_e32 v5, v83
	v_mov_b32_e32 v7, v77
	v_lshlrev_b32_e32 v4, 16, v4
	s_waitcnt vmcnt(0)
	v_add_f32_e32 v4, v5, v4
	v_cmp_nlt_f32_e32 vcc, s67, v4
	s_and_saveexec_b64 s[2:3], vcc
	s_cbranch_execz .LBB0_559
	v_cmp_ngt_f32_e32 vcc, s68, v4
	v_mul_f32_e32 v4, 0x3fb8aa3b, v4
	v_exp_f32_e32 v4, v4
	s_and_saveexec_b64 s[4:5], vcc
	s_cbranch_execz .LBB0_558
	v_add_f32_e32 v4, 1.0, v4
	v_cmp_gt_f32_e32 vcc, s65, v4
	s_mov_b32 s9, 0x3f317217
	s_nop 0
	v_cndmask_b32_e64 v5, 0, 32, vcc
	v_ldexp_f32 v4, v4, v5
	v_log_f32_e32 v4, v4
	s_nop 0
	v_mul_f32_e32 v5, 0x3f317217, v4
	v_fma_f32 v5, v4, s9, -v5
	v_fmac_f32_e32 v5, 0x3377d1cf, v4
	s_mov_b32 s9, 0x7f800000
	v_fmac_f32_e32 v5, 0x3f317217, v4
	v_cmp_lt_f32_e64 s[42:43], |v4|, s9
	s_nop 1
	v_cndmask_b32_e64 v4, v4, v5, s[42:43]
	v_cndmask_b32_e32 v5, 0, v217, vcc
	v_sub_f32_e32 v4, v4, v5

; __device__ __forceinline__ float bf2f(bf16 b) { return __uint_as_float(((unsigned)b) << 16); }
; __device__ __forceinline__ float sigmoid_(float x) { return __builtin_amdgcn_rcpf(1.f + __expf(-x)); }
; __device__ __forceinline__ float softplus_(float x) { return x > 15.f ? x : (x < -15.f ? __expf(x) : __logf(1.f + __expf(x))); }
; __device__ __forceinline__ void phase_dn_prep(const KP kp, const int bid, const int G, int j, LAS unsigned char* lds, int tid0) {
;     ...
;         if (wave == 0) { const size_t ro = (size_t)(row0 + lane) * NAB;
;             float gv = -__expf(kp.in(15)[j * 8 + h]) * softplus_(bf2f(U[ro + 7176 + h]) + kp.in(16)[j * 8 + h]);
; #pragma unroll
;             for (int o = 1; o < 64; o <<= 1) { const float tt = __shfl_up(gv, o); if (lane >= o) gv += tt; }
;             GLs[lane] = gv; BLs[lane] = sigmoid_(bf2f(U[ro + 7168 + h])); }
.LBB0_559:
	s_or_b64 exec, exec, s[2:3]
	s_nop 0
	v_mul_f32_e32 v0, 0x3fb8aa3b, v0
	s_nop 0
	s_nop 0
	v_exp_f32_e32 v0, v0
	v_and_b32_e32 v5, 64, v216
	v_add_u32_e32 v6, -1, v216
	v_cmp_lt_i32_e32 vcc, v6, v5
	v_mul_f32_e64 v3, v4, -v0
	s_waitcnt vmcnt(0)
	v_lshlrev_b32_e32 v2, 16, v7
	v_cndmask_b32_e32 v6, v6, v216, vcc
	v_lshlrev_b32_e32 v6, 2, v6
	ds_bpermute_b32 v6, v6, v3
	v_cmp_eq_u32_e32 vcc, 0, v68
	v_mul_f32_e32 v2, 0xbfb8aa3b, v2
	v_exp_f32_e32 v2, v2
	s_waitcnt lgkmcnt(0)
	v_fma_f32 v0, v4, -v0, v6
	v_cndmask_b32_e32 v0, v0, v3, vcc
	v_add_u32_e32 v3, -2, v216
	v_cmp_lt_i32_e32 vcc, v3, v5
	v_add_f32_e32 v2, 1.0, v2
	v_rcp_f32_e32 v2, v2
	v_cndmask_b32_e32 v3, v3, v216, vcc
	v_lshlrev_b32_e32 v3, 2, v3
	ds_bpermute_b32 v3, v3, v0
	v_cmp_gt_u32_e32 vcc, 2, v68
	s_waitcnt lgkmcnt(0)
	v_add_f32_e32 v3, v0, v3
	v_cndmask_b32_e32 v0, v3, v0, vcc
	v_add_u32_e32 v3, -4, v216
	v_cmp_lt_i32_e32 vcc, v3, v5
	s_nop 1
	v_cndmask_b32_e32 v3, v3, v216, vcc
	v_lshlrev_b32_e32 v3, 2, v3
	ds_bpermute_b32 v3, v3, v0
	v_cmp_gt_u32_e32 vcc, 4, v68
	s_waitcnt lgkmcnt(0)
	v_add_f32_e32 v3, v0, v3
	v_cndmask_b32_e32 v0, v3, v0, vcc
	v_add_u32_e32 v3, -8, v216
	v_cmp_lt_i32_e32 vcc, v3, v5
	s_nop 1
	v_cndmask_b32_e32 v3, v3, v216, vcc
	v_lshlrev_b32_e32 v3, 2, v3
	ds_bpermute_b32 v3, v3, v0
	v_cmp_gt_u32_e32 vcc, 8, v68
	s_waitcnt lgkmcnt(0)
	v_add_f32_e32 v3, v0, v3
	v_cndmask_b32_e32 v0, v3, v0, vcc
	v_add_u32_e32 v3, -16, v216
	v_cmp_lt_i32_e32 vcc, v3, v5
	s_nop 1
	v_cndmask_b32_e32 v3, v3, v216, vcc
	v_lshlrev_b32_e32 v3, 2, v3
	ds_bpermute_b32 v3, v3, v0
	v_cmp_gt_u32_e32 vcc, 16, v68
	s_waitcnt lgkmcnt(0)
	v_add_f32_e32 v3, v0, v3
	v_cndmask_b32_e32 v0, v3, v0, vcc
	v_subrev_u32_e32 v3, 32, v216
	v_cmp_lt_i32_e32 vcc, v3, v5
	s_nop 1
	v_cndmask_b32_e32 v3, v3, v216, vcc
	v_lshlrev_b32_e32 v3, 2, v3
	ds_bpermute_b32 v3, v3, v0
	v_cmp_gt_u32_e32 vcc, 32, v68
	s_waitcnt lgkmcnt(0)
	v_add_f32_e32 v3, v0, v3
	v_cndmask_b32_e32 v0, v3, v0, vcc
	v_lshl_add_u32 v3, v68, 2, 0
	ds_write2st64_b32 v3, v0, v2 offset0:68 offset1:69

; __global__ void __launch_bounds__(NTHR, 2) mega_fwd(Args A) {
	.amdhsa_kernel _Z8mega_fwd4Args
		.amdhsa_group_segment_fixed_size 0
		.amdhsa_private_segment_fixed_size 0
		.amdhsa_kernarg_size 600
		.amdhsa_user_sgpr_count 2
		.amdhsa_user_sgpr_dispatch_ptr 0
		.amdhsa_user_sgpr_queue_ptr 0
		.amdhsa_user_sgpr_kernarg_segment_ptr 1
		.amdhsa_user_sgpr_dispatch_id 0
		.amdhsa_user_sgpr_kernarg_preload_length 0
		.amdhsa_user_sgpr_kernarg_preload_offset 0
		.amdhsa_user_sgpr_private_segment_size 0
		.amdhsa_uses_dynamic_stack 0
		.amdhsa_enable_private_segment 0
		.amdhsa_system_sgpr_workgroup_id_x 1
		.amdhsa_system_sgpr_workgroup_id_y 0
		.amdhsa_system_sgpr_workgroup_id_z 0
		.amdhsa_system_sgpr_workgroup_info 0
		.amdhsa_system_vgpr_workitem_id 2
		.amdhsa_next_free_vgpr 256
		.amdhsa_next_free_sgpr 102
		.amdhsa_accum_offset 256
		.amdhsa_reserve_vcc 1
		.amdhsa_float_round_mode_32 0
		.amdhsa_float_round_mode_16_64 0
		.amdhsa_float_denorm_mode_32 3
		.amdhsa_float_denorm_mode_16_64 3
		.amdhsa_dx10_clamp 1
		.amdhsa_ieee_mode 1
		.amdhsa_fp16_overflow 0
		.amdhsa_tg_split 0
		.amdhsa_exception_fp_ieee_invalid_op 0
		.amdhsa_exception_fp_denorm_src 0
		.amdhsa_exception_fp_ieee_div_zero 0
		.amdhsa_exception_fp_ieee_overflow 0
		.amdhsa_exception_fp_ieee_underflow 0
		.amdhsa_exception_fp_ieee_inexact 0
		.amdhsa_exception_int_div_zero 0
	.end_amdhsa_kernel

; __global__ void __launch_bounds__(NTHR, 2) mega_fwd(Args A) {
amdhsa.kernels:
  - .agpr_count:     0
    .args:
      - .offset:         0
        .size:           344
        .value_kind:     by_value
      - .offset:         344
        .size:           4
        .value_kind:     hidden_block_count_x
      - .offset:         348
        .size:           4
        .value_kind:     hidden_block_count_y
      - .offset:         352
        .size:           4
        .value_kind:     hidden_block_count_z
      - .offset:         356
        .size:           2
        .value_kind:     hidden_group_size_x
      - .offset:         358
        .size:           2
        .value_kind:     hidden_group_size_y
      - .offset:         360
        .size:           2
        .value_kind:     hidden_group_size_z
      - .offset:         362
        .size:           2
        .value_kind:     hidden_remainder_x
      - .offset:         364
        .size:           2
        .value_kind:     hidden_remainder_y
      - .offset:         366
        .size:           2
        .value_kind:     hidden_remainder_z
      - .offset:         384
        .size:           8
        .value_kind:     hidden_global_offset_x
      - .offset:         392
        .size:           8
        .value_kind:     hidden_global_offset_y
      - .offset:         400
        .size:           8
        .value_kind:     hidden_global_offset_z
      - .offset:         408
        .size:           2
        .value_kind:     hidden_grid_dims
      - .offset:         432
        .size:           8
        .value_kind:     hidden_multigrid_sync_arg
      - .offset:         464
        .size:           4
        .value_kind:     hidden_dynamic_lds_size
    .group_segment_fixed_size: 0
    .kernarg_segment_align: 8
    .kernarg_segment_size: 600
    .language:       OpenCL C
    .language_version:
      - 2
      - 0
    .max_flat_workgroup_size: 512
    .name:           _Z8mega_fwd4Args
    .private_segment_fixed_size: 0
    .sgpr_count:     108
    .sgpr_spill_count: 340
    .symbol:         _Z8mega_fwd4Args.kd
    .uniform_work_group_size: 1
    .uses_dynamic_stack: false
    .vgpr_count:     256
    .vgpr_spill_count: 0
    .wavefront_size: 64
